# G1 q/k epilogue: cross-lane reductions via permlane swaps and DPP row ops instead of serialized ds_bpermute chains (on top of v66)
# speedup vs baseline: 1.0350x; 1.0062x over previous
.LBB0_267:
	s_andn2_b64 vcc, exec, s[74:75]
	s_cbranch_vccnz .LBB0_336
	s_cmp_eq_u32 s15, 2
	s_cselect_b64 vcc, -1, 0
	s_and_b64 s[4:5], vcc, exec
	s_cselect_b32 s4, s8, s10
	s_cselect_b32 s5, s9, s11
	s_add_u32 s4, s4, s28
	s_addc_u32 s5, s5, 0
	v_ashrrev_i32_e32 v151, 31, v150
	v_lshl_add_u64 v[132:133], v[150:151], 2, s[4:5]
	global_load_dwordx4 v[128:131], v[132:133], off offset:16
	s_nop 0
	global_load_dwordx4 v[132:135], v[132:133], off
	v_cmp_gt_u32_e64 s[4:5], 16, v185
	v_add_lshl_u32 v144, v185, s84, 5
	v_mul_f32_e32 v202, v125, v125
	v_mul_f32_e32 v234, v127, v127
	v_fmac_f32_e32 v202, v124, v124
	v_fmac_f32_e32 v234, v126, v126
	v_add_f32_e32 v202, v202, v234
	v_mul_f32_e32 v234, v121, v121
	v_fmac_f32_e32 v234, v120, v120
	v_add_f32_e32 v202, v202, v234
	v_mul_f32_e32 v234, v123, v123
	v_fmac_f32_e32 v234, v122, v122
	v_add_f32_e32 v202, v234, v202
	v_mul_f32_e32 v203, v117, v117
	v_mul_f32_e32 v235, v119, v119
	v_fmac_f32_e32 v203, v116, v116
	v_fmac_f32_e32 v235, v118, v118
	v_add_f32_e32 v203, v203, v235
	v_mul_f32_e32 v235, v113, v113
	v_fmac_f32_e32 v235, v112, v112
	v_add_f32_e32 v203, v203, v235
	v_mul_f32_e32 v235, v115, v115
	v_fmac_f32_e32 v235, v114, v114
	v_add_f32_e32 v203, v235, v203
	v_mul_f32_e32 v204, v109, v109
	v_mul_f32_e32 v234, v111, v111
	v_fmac_f32_e32 v204, v108, v108
	v_fmac_f32_e32 v234, v110, v110
	v_add_f32_e32 v204, v204, v234
	v_mul_f32_e32 v234, v105, v105
	v_fmac_f32_e32 v234, v104, v104
	v_add_f32_e32 v204, v204, v234
	v_mul_f32_e32 v234, v107, v107
	v_fmac_f32_e32 v234, v106, v106
	v_add_f32_e32 v204, v234, v204
	v_mul_f32_e32 v205, v101, v101
	v_mul_f32_e32 v235, v103, v103
	v_fmac_f32_e32 v205, v100, v100
	v_fmac_f32_e32 v235, v102, v102
	v_add_f32_e32 v205, v205, v235
	v_mul_f32_e32 v235, v97, v97
	v_fmac_f32_e32 v235, v96, v96
	v_add_f32_e32 v205, v205, v235
	v_mul_f32_e32 v235, v99, v99
	v_fmac_f32_e32 v235, v98, v98
	v_add_f32_e32 v205, v235, v205
	v_mul_f32_e32 v206, v93, v93
	v_mul_f32_e32 v234, v95, v95
	v_fmac_f32_e32 v206, v92, v92
	v_fmac_f32_e32 v234, v94, v94
	v_add_f32_e32 v206, v206, v234
	v_mul_f32_e32 v234, v89, v89
	v_fmac_f32_e32 v234, v88, v88
	v_add_f32_e32 v206, v206, v234
	v_mul_f32_e32 v234, v91, v91
	v_fmac_f32_e32 v234, v90, v90
	v_add_f32_e32 v206, v234, v206
	v_mul_f32_e32 v207, v85, v85
	v_mul_f32_e32 v235, v87, v87
	v_fmac_f32_e32 v207, v84, v84
	v_fmac_f32_e32 v235, v86, v86
	v_add_f32_e32 v207, v207, v235
	v_mul_f32_e32 v235, v81, v81
	v_fmac_f32_e32 v235, v80, v80
	v_add_f32_e32 v207, v207, v235
	v_mul_f32_e32 v235, v83, v83
	v_fmac_f32_e32 v235, v82, v82
	v_add_f32_e32 v207, v235, v207
	v_mul_f32_e32 v208, v77, v77
	v_mul_f32_e32 v234, v79, v79
	v_fmac_f32_e32 v208, v76, v76
	v_fmac_f32_e32 v234, v78, v78
	v_add_f32_e32 v208, v208, v234
	v_mul_f32_e32 v234, v73, v73
	v_fmac_f32_e32 v234, v72, v72
	v_add_f32_e32 v208, v208, v234
	v_mul_f32_e32 v234, v75, v75
	v_fmac_f32_e32 v234, v74, v74
	v_add_f32_e32 v208, v234, v208
	v_mul_f32_e32 v209, v69, v69
	v_mul_f32_e32 v235, v71, v71
	v_fmac_f32_e32 v209, v68, v68
	v_fmac_f32_e32 v235, v70, v70
	v_add_f32_e32 v209, v209, v235
	v_mul_f32_e32 v235, v65, v65
	v_fmac_f32_e32 v235, v64, v64
	v_add_f32_e32 v209, v209, v235
	v_mul_f32_e32 v235, v67, v67
	v_fmac_f32_e32 v235, v66, v66
	v_add_f32_e32 v209, v235, v209
	v_mul_f32_e32 v210, v61, v61
	v_mul_f32_e32 v234, v63, v63
	v_fmac_f32_e32 v210, v60, v60
	v_fmac_f32_e32 v234, v62, v62
	v_add_f32_e32 v210, v210, v234
	v_mul_f32_e32 v234, v57, v57
	v_fmac_f32_e32 v234, v56, v56
	v_add_f32_e32 v210, v210, v234
	v_mul_f32_e32 v234, v59, v59
	v_fmac_f32_e32 v234, v58, v58
	v_add_f32_e32 v210, v234, v210
	v_mul_f32_e32 v211, v53, v53
	v_mul_f32_e32 v235, v55, v55
	v_fmac_f32_e32 v211, v52, v52
	v_fmac_f32_e32 v235, v54, v54
	v_add_f32_e32 v211, v211, v235
	v_mul_f32_e32 v235, v49, v49
	v_fmac_f32_e32 v235, v48, v48
	v_add_f32_e32 v211, v211, v235
	v_mul_f32_e32 v235, v51, v51
	v_fmac_f32_e32 v235, v50, v50
	v_add_f32_e32 v211, v235, v211
	v_mul_f32_e32 v212, v45, v45
	v_mul_f32_e32 v234, v47, v47
	v_fmac_f32_e32 v212, v44, v44
	v_fmac_f32_e32 v234, v46, v46
	v_add_f32_e32 v212, v212, v234
	v_mul_f32_e32 v234, v41, v41
	v_fmac_f32_e32 v234, v40, v40
	v_add_f32_e32 v212, v212, v234
	v_mul_f32_e32 v234, v43, v43
	v_fmac_f32_e32 v234, v42, v42
	v_add_f32_e32 v212, v234, v212
	v_mul_f32_e32 v213, v37, v37
	v_mul_f32_e32 v235, v39, v39
	v_fmac_f32_e32 v213, v36, v36
	v_fmac_f32_e32 v235, v38, v38
	v_add_f32_e32 v213, v213, v235
	v_mul_f32_e32 v235, v33, v33
	v_fmac_f32_e32 v235, v32, v32
	v_add_f32_e32 v213, v213, v235
	v_mul_f32_e32 v235, v35, v35
	v_fmac_f32_e32 v235, v34, v34
	v_add_f32_e32 v213, v235, v213
	v_mul_f32_e32 v214, v29, v29
	v_mul_f32_e32 v234, v31, v31
	v_fmac_f32_e32 v214, v28, v28
	v_fmac_f32_e32 v234, v30, v30
	v_add_f32_e32 v214, v214, v234
	v_mul_f32_e32 v234, v25, v25
	v_fmac_f32_e32 v234, v24, v24
	v_add_f32_e32 v214, v214, v234
	v_mul_f32_e32 v234, v27, v27
	v_fmac_f32_e32 v234, v26, v26
	v_add_f32_e32 v214, v234, v214
	v_mul_f32_e32 v215, v21, v21
	v_mul_f32_e32 v235, v23, v23
	v_fmac_f32_e32 v215, v20, v20
	v_fmac_f32_e32 v235, v22, v22
	v_add_f32_e32 v215, v215, v235
	v_mul_f32_e32 v235, v17, v17
	v_fmac_f32_e32 v235, v16, v16
	v_add_f32_e32 v215, v215, v235
	v_mul_f32_e32 v235, v19, v19
	v_fmac_f32_e32 v235, v18, v18
	v_add_f32_e32 v215, v235, v215
	v_mul_f32_e32 v216, v13, v13
	v_mul_f32_e32 v234, v15, v15
	v_fmac_f32_e32 v216, v12, v12
	v_fmac_f32_e32 v234, v14, v14
	v_add_f32_e32 v216, v216, v234
	v_mul_f32_e32 v234, v9, v9
	v_fmac_f32_e32 v234, v8, v8
	v_add_f32_e32 v216, v216, v234
	v_mul_f32_e32 v234, v11, v11
	v_fmac_f32_e32 v234, v10, v10
	v_add_f32_e32 v216, v234, v216
	v_mul_f32_e32 v217, v5, v5
	v_mul_f32_e32 v235, v7, v7
	v_fmac_f32_e32 v217, v4, v4
	v_fmac_f32_e32 v235, v6, v6
	v_add_f32_e32 v217, v217, v235
	v_mul_f32_e32 v235, v1, v1
	v_fmac_f32_e32 v235, v0, v0
	v_add_f32_e32 v217, v217, v235
	v_mul_f32_e32 v235, v3, v3
	v_fmac_f32_e32 v235, v2, v2
	v_add_f32_e32 v217, v235, v217
	v_mov_b32_e32 v218, v202
	v_mov_b32_e32 v219, v203
	v_mov_b32_e32 v220, v204
	v_mov_b32_e32 v221, v205
	v_mov_b32_e32 v222, v206
	v_mov_b32_e32 v223, v207
	v_mov_b32_e32 v224, v208
	v_mov_b32_e32 v225, v209
	v_mov_b32_e32 v226, v210
	v_mov_b32_e32 v227, v211
	v_mov_b32_e32 v228, v212
	v_mov_b32_e32 v229, v213
	v_mov_b32_e32 v230, v214
	v_mov_b32_e32 v231, v215
	v_mov_b32_e32 v232, v216
	v_mov_b32_e32 v233, v217
	v_permlane16_swap_b32_e32 v202, v218
	v_permlane16_swap_b32_e32 v203, v219
	v_permlane16_swap_b32_e32 v204, v220
	v_permlane16_swap_b32_e32 v205, v221
	v_permlane16_swap_b32_e32 v206, v222
	v_permlane16_swap_b32_e32 v207, v223
	v_permlane16_swap_b32_e32 v208, v224
	v_permlane16_swap_b32_e32 v209, v225
	v_permlane16_swap_b32_e32 v210, v226
	v_permlane16_swap_b32_e32 v211, v227
	v_permlane16_swap_b32_e32 v212, v228
	v_permlane16_swap_b32_e32 v213, v229
	v_permlane16_swap_b32_e32 v214, v230
	v_permlane16_swap_b32_e32 v215, v231
	v_permlane16_swap_b32_e32 v216, v232
	v_permlane16_swap_b32_e32 v217, v233
	v_add_f32_e32 v202, v202, v218
	v_add_f32_e32 v203, v203, v219
	v_add_f32_e32 v204, v204, v220
	v_add_f32_e32 v205, v205, v221
	v_add_f32_e32 v206, v206, v222
	v_add_f32_e32 v207, v207, v223
	v_add_f32_e32 v208, v208, v224
	v_add_f32_e32 v209, v209, v225
	v_add_f32_e32 v210, v210, v226
	v_add_f32_e32 v211, v211, v227
	v_add_f32_e32 v212, v212, v228
	v_add_f32_e32 v213, v213, v229
	v_add_f32_e32 v214, v214, v230
	v_add_f32_e32 v215, v215, v231
	v_add_f32_e32 v216, v216, v232
	v_add_f32_e32 v217, v217, v233
	v_mov_b32_e32 v218, v202
	v_mov_b32_e32 v219, v203
	v_mov_b32_e32 v220, v204
	v_mov_b32_e32 v221, v205
	v_mov_b32_e32 v222, v206
	v_mov_b32_e32 v223, v207
	v_mov_b32_e32 v224, v208
	v_mov_b32_e32 v225, v209
	v_mov_b32_e32 v226, v210
	v_mov_b32_e32 v227, v211
	v_mov_b32_e32 v228, v212
	v_mov_b32_e32 v229, v213
	v_mov_b32_e32 v230, v214
	v_mov_b32_e32 v231, v215
	v_mov_b32_e32 v232, v216
	v_mov_b32_e32 v233, v217
	v_permlane32_swap_b32_e32 v202, v218
	v_permlane32_swap_b32_e32 v203, v219
	v_permlane32_swap_b32_e32 v204, v220
	v_permlane32_swap_b32_e32 v205, v221
	v_permlane32_swap_b32_e32 v206, v222
	v_permlane32_swap_b32_e32 v207, v223
	v_permlane32_swap_b32_e32 v208, v224
	v_permlane32_swap_b32_e32 v209, v225
	v_permlane32_swap_b32_e32 v210, v226
	v_permlane32_swap_b32_e32 v211, v227
	v_permlane32_swap_b32_e32 v212, v228
	v_permlane32_swap_b32_e32 v213, v229
	v_permlane32_swap_b32_e32 v214, v230
	v_permlane32_swap_b32_e32 v215, v231
	v_permlane32_swap_b32_e32 v216, v232
	v_permlane32_swap_b32_e32 v217, v233
	v_add_f32_e32 v202, v202, v218
	v_add_f32_e32 v203, v203, v219
	v_add_f32_e32 v204, v204, v220
	v_add_f32_e32 v205, v205, v221
	v_add_f32_e32 v206, v206, v222
	v_add_f32_e32 v207, v207, v223
	v_add_f32_e32 v208, v208, v224
	v_add_f32_e32 v209, v209, v225
	v_add_f32_e32 v210, v210, v226
	v_add_f32_e32 v211, v211, v227
	v_add_f32_e32 v212, v212, v228
	v_add_f32_e32 v213, v213, v229
	v_add_f32_e32 v214, v214, v230
	v_add_f32_e32 v215, v215, v231
	v_add_f32_e32 v216, v216, v232
	v_add_f32_e32 v217, v217, v233
	v_add_u32_e32 v218, s92, v144
	v_add_u32_e32 v219, s93, v144
	v_add_u32_e32 v220, s94, v144
	v_add_u32_e32 v221, s95, v144
	v_add_u32_e32 v222, s96, v144
	v_add_u32_e32 v223, s97, v144
	v_add_u32_e32 v224, s50, v144
	v_add_u32_e32 v225, s51, v144
	s_and_saveexec_b64 s[74:75], s[4:5]
	ds_write_b32 v218, v202
	ds_write_b32 v218, v203 offset:16
	ds_write_b32 v219, v204
	ds_write_b32 v219, v205 offset:16
	ds_write_b32 v220, v206
	ds_write_b32 v220, v207 offset:16
	ds_write_b32 v221, v208
	ds_write_b32 v221, v209 offset:16
	ds_write_b32 v222, v210
	ds_write_b32 v222, v211 offset:16
	ds_write_b32 v223, v212
	ds_write_b32 v223, v213 offset:16
	ds_write_b32 v224, v214
	ds_write_b32 v224, v215 offset:16
	ds_write_b32 v225, v216
	ds_write_b32 v225, v217 offset:16
.LBB0_300:
	s_or_b64 exec, exec, s[74:75]
	v_or_b32_e32 v144, s84, v186
	v_lshl_add_u32 v144, v144, 5, 0
	s_waitcnt lgkmcnt(0)
	s_barrier
	v_add_u32_e32 v151, 0x20400, v144
	ds_read_b128 v[156:159], v151
	ds_read_b128 v[188:191], v151 offset:16
	v_ashrrev_i32_e32 v155, 31, v154
	s_mov_b32 s4, 0x40000
	s_cmp_lg_u32 s15, 3
	s_waitcnt lgkmcnt(0)
	v_mov_b32_e32 v180, v157
	v_mov_b32_e32 v181, v158
	v_mov_b32_e32 v157, v159
	v_pk_add_f32 v[156:157], v[180:181], v[156:157]
	s_nop 0
	v_add_f32_e32 v151, v156, v157
	v_fmamk_f32 v151, v151, 0x3c000000, v183
	v_rsq_f32_e32 v196, v151
	v_mov_b32_e32 v156, v189
	v_mov_b32_e32 v157, v190
	v_mov_b32_e32 v189, v191
	v_add_u32_e32 v151, 0x20600, v144
	v_pk_add_f32 v[180:181], v[156:157], v[188:189]
	ds_read_b128 v[156:159], v151
	ds_read_b128 v[188:191], v151 offset:16
	v_add_f32_e32 v153, v180, v181
	v_fmamk_f32 v153, v153, 0x3c000000, v183
	v_rsq_f32_e32 v198, v153
	s_waitcnt lgkmcnt(0)
	v_mov_b32_e32 v180, v157
	v_mov_b32_e32 v181, v158
	v_mov_b32_e32 v157, v159
	v_pk_add_f32 v[156:157], v[180:181], v[156:157]
	v_pk_mul_f32 v[124:125], v[124:125], v[196:197] op_sel_hi:[1,0]
	v_add_f32_e32 v151, v156, v157
	v_fmamk_f32 v151, v151, 0x3c000000, v183
	v_rsq_f32_e32 v182, v151
	v_mov_b32_e32 v156, v189
	v_mov_b32_e32 v157, v190
	v_mov_b32_e32 v189, v191
	v_add_u32_e32 v151, 0x20800, v144
	v_pk_add_f32 v[180:181], v[156:157], v[188:189]
	ds_read_b128 v[156:159], v151
	ds_read_b128 v[188:191], v151 offset:16
	v_add_f32_e32 v153, v180, v181
	v_fmamk_f32 v153, v153, 0x3c000000, v183
	v_rsq_f32_e32 v178, v153
	s_waitcnt lgkmcnt(0)
	v_mov_b32_e32 v180, v157
	v_mov_b32_e32 v181, v158
	v_mov_b32_e32 v157, v159
	v_pk_add_f32 v[156:157], v[180:181], v[156:157]
	v_pk_mul_f32 v[126:127], v[126:127], v[196:197] op_sel_hi:[1,0]
	v_add_f32_e32 v151, v156, v157
	v_fmamk_f32 v151, v151, 0x3c000000, v183
	v_rsq_f32_e32 v176, v151
	v_mov_b32_e32 v156, v189
	v_mov_b32_e32 v157, v190
	v_mov_b32_e32 v189, v191
	v_add_u32_e32 v151, 0x20a00, v144
	v_pk_add_f32 v[180:181], v[156:157], v[188:189]
	ds_read_b128 v[156:159], v151
	ds_read_b128 v[188:191], v151 offset:16
	v_add_f32_e32 v153, v180, v181
	v_fmamk_f32 v153, v153, 0x3c000000, v183
	v_rsq_f32_e32 v174, v153
	s_waitcnt lgkmcnt(0)
	v_mov_b32_e32 v180, v157
	v_mov_b32_e32 v181, v158
	v_mov_b32_e32 v157, v159
	v_pk_add_f32 v[156:157], v[180:181], v[156:157]
	v_pk_mul_f32 v[116:117], v[116:117], v[198:199] op_sel_hi:[1,0]
	v_add_f32_e32 v151, v156, v157
	v_fmamk_f32 v151, v151, 0x3c000000, v183
	v_rsq_f32_e32 v172, v151
	v_mov_b32_e32 v156, v189
	v_mov_b32_e32 v157, v190
	v_mov_b32_e32 v189, v191
	v_add_u32_e32 v151, 0x21400, v144
	v_pk_add_f32 v[180:181], v[156:157], v[188:189]
	ds_read_b128 v[156:159], v151
	ds_read_b128 v[188:191], v151 offset:16
	v_add_f32_e32 v153, v180, v181
	v_fmamk_f32 v153, v153, 0x3c000000, v183
	v_rsq_f32_e32 v170, v153
	s_waitcnt lgkmcnt(0)
	v_mov_b32_e32 v180, v157
	v_mov_b32_e32 v181, v158
	v_mov_b32_e32 v157, v159
	v_pk_add_f32 v[156:157], v[180:181], v[156:157]
	v_pk_mul_f32 v[118:119], v[118:119], v[198:199] op_sel_hi:[1,0]
	v_add_f32_e32 v151, v156, v157
	v_fmamk_f32 v151, v151, 0x3c000000, v183
	v_rsq_f32_e32 v168, v151
	v_mov_b32_e32 v156, v189
	v_mov_b32_e32 v157, v190
	v_mov_b32_e32 v189, v191
	v_add_u32_e32 v151, 0x21600, v144
	v_pk_add_f32 v[180:181], v[156:157], v[188:189]
	ds_read_b128 v[156:159], v151
	ds_read_b128 v[188:191], v151 offset:16
	v_add_f32_e32 v153, v180, v181
	v_fmamk_f32 v153, v153, 0x3c000000, v183
	v_rsq_f32_e32 v166, v153
	s_waitcnt lgkmcnt(0)
	v_mov_b32_e32 v180, v157
	v_mov_b32_e32 v181, v158
	v_mov_b32_e32 v157, v159
	v_pk_add_f32 v[156:157], v[180:181], v[156:157]
	v_pk_mul_f32 v[108:109], v[108:109], v[182:183] op_sel_hi:[1,0]
	v_add_f32_e32 v151, v156, v157
	v_fmamk_f32 v151, v151, 0x3c000000, v183
	v_rsq_f32_e32 v164, v151
	v_mov_b32_e32 v156, v189
	v_mov_b32_e32 v157, v190
	v_mov_b32_e32 v189, v191
	v_add_u32_e32 v151, 0x21800, v144
	v_pk_add_f32 v[180:181], v[156:157], v[188:189]
	ds_read_b128 v[156:159], v151
	ds_read_b128 v[188:191], v151 offset:16
	v_add_f32_e32 v153, v180, v181
	v_add_u32_e32 v144, 0x21a00, v144
	ds_read_b128 v[192:195], v144 offset:16
	s_waitcnt lgkmcnt(0)
	v_mov_b32_e32 v180, v157
	v_mov_b32_e32 v181, v158
	v_mov_b32_e32 v157, v159
	v_pk_add_f32 v[156:157], v[180:181], v[156:157]
	v_mov_b32_e32 v180, v193
	v_add_f32_e32 v151, v156, v157
	v_mov_b32_e32 v156, v189
	v_mov_b32_e32 v157, v190
	v_mov_b32_e32 v189, v191
	v_pk_add_f32 v[156:157], v[156:157], v[188:189]
	ds_read_b128 v[188:191], v144
	v_fmamk_f32 v151, v151, 0x3c000000, v183
	v_rsq_f32_e32 v160, v151
	v_add_f32_e32 v151, v156, v157
	v_mov_b32_e32 v181, v194
	s_waitcnt lgkmcnt(0)
	v_mov_b32_e32 v156, v189
	v_mov_b32_e32 v157, v190
	v_mov_b32_e32 v189, v191
	v_pk_add_f32 v[156:157], v[156:157], v[188:189]
	v_mov_b32_e32 v193, v195
	v_add_f32_e32 v144, v156, v157
	v_fmamk_f32 v144, v144, 0x3c000000, v183
	v_pk_add_f32 v[180:181], v[180:181], v[192:193]
	v_fmamk_f32 v153, v153, 0x3c000000, v183
	v_rsq_f32_e32 v156, v144
	v_add_f32_e32 v144, v180, v181
	v_cndmask_b32_e32 v180, 1.0, v184, vcc
	v_rsq_f32_e32 v162, v153
	s_waitcnt vmcnt(0)
	v_pk_mul_f32 v[132:133], v[180:181], v[132:133] op_sel_hi:[0,1]
	v_ashrrev_i32_e32 v153, 31, v152
	v_pk_mul_f32 v[134:135], v[180:181], v[134:135] op_sel_hi:[0,1]
	v_pk_mul_f32 v[128:129], v[180:181], v[128:129] op_sel_hi:[0,1]
	v_pk_mul_f32 v[130:131], v[180:181], v[130:131] op_sel_hi:[0,1]
	v_lshl_add_u64 v[180:181], v[154:155], 1, s[72:73]
	v_lshlrev_b64 v[154:155], 11, v[152:153]
	v_pk_mul_f32 v[188:189], v[132:133], v[124:125]
	v_lshl_add_u64 v[154:155], v[180:181], 0, v[154:155]
	v_pk_mul_f32 v[190:191], v[134:135], v[126:127]
	v_pk_mul_f32 v[192:193], v[120:121], v[196:197] op_sel_hi:[1,0]
	v_pk_mul_f32 v[194:195], v[122:123], v[196:197] op_sel_hi:[1,0]
	v_cvt_pk_bf16_f32 v188, v188, v189
	v_cvt_pk_bf16_f32 v189, v190, v191
	v_pk_mul_f32 v[200:201], v[128:129], v[192:193]
	v_pk_mul_f32 v[196:197], v[130:131], v[194:195]
	v_cvt_pk_bf16_f32 v190, v200, v201
	v_pk_fma_f32 v[122:123], v[134:135], v[126:127], 0 op_sel_hi:[1,1,0]
	v_cvt_pk_bf16_f32 v191, v196, v197
	global_store_dwordx4 v[154:155], v[188:191], off nt
	v_pk_fma_f32 v[120:121], v[132:133], v[124:125], 0 op_sel_hi:[1,1,0]
	v_pk_fma_f32 v[126:127], v[130:131], v[194:195], 0 op_sel_hi:[1,1,0]
	v_pk_mul_f32 v[188:189], v[132:133], v[116:117]
	v_pk_fma_f32 v[124:125], v[128:129], v[192:193], 0 op_sel_hi:[1,1,0]
	v_pk_mul_f32 v[190:191], v[134:135], v[118:119]
	v_pk_mul_f32 v[192:193], v[112:113], v[198:199] op_sel_hi:[1,0]
	v_pk_mul_f32 v[194:195], v[114:115], v[198:199] op_sel_hi:[1,0]
	v_cvt_pk_bf16_f32 v188, v188, v189
	v_pk_mul_f32 v[198:199], v[128:129], v[192:193]
	v_pk_mul_f32 v[196:197], v[130:131], v[194:195]
	v_cvt_pk_bf16_f32 v189, v190, v191
	v_cvt_pk_bf16_f32 v190, v198, v199
	v_pk_fma_f32 v[114:115], v[134:135], v[118:119], 0 op_sel_hi:[1,1,0]
	v_cvt_pk_bf16_f32 v191, v196, v197
	global_store_dwordx4 v[154:155], v[188:191], off offset:256 nt
	v_pk_fma_f32 v[112:113], v[132:133], v[116:117], 0 op_sel_hi:[1,1,0]
	v_pk_fma_f32 v[118:119], v[130:131], v[194:195], 0 op_sel_hi:[1,1,0]
	v_or_b32_e32 v188, 16, v152
	v_pk_fma_f32 v[116:117], v[128:129], v[192:193], 0 op_sel_hi:[1,1,0]
	v_ashrrev_i32_e32 v189, 31, v188
	v_lshlrev_b64 v[188:189], 11, v[188:189]
	v_pk_mul_f32 v[110:111], v[110:111], v[182:183] op_sel_hi:[1,0]
	v_pk_mul_f32 v[194:195], v[104:105], v[182:183] op_sel_hi:[1,0]
	v_pk_mul_f32 v[196:197], v[106:107], v[182:183] op_sel_hi:[1,0]
	v_lshl_add_u64 v[188:189], v[180:181], 0, v[188:189]
	v_pk_mul_f32 v[190:191], v[134:135], v[110:111]
	v_pk_mul_f32 v[192:193], v[132:133], v[108:109]
	v_pk_mul_f32 v[198:199], v[130:131], v[196:197]
	v_pk_mul_f32 v[200:201], v[128:129], v[194:195]
	v_pk_fma_f32 v[106:107], v[134:135], v[110:111], v[122:123]
	v_pk_fma_f32 v[104:105], v[132:133], v[108:109], v[120:121]
	v_cvt_pk_bf16_f32 v120, v192, v193
	v_cvt_pk_bf16_f32 v121, v190, v191
	v_cvt_pk_bf16_f32 v122, v200, v201
	v_cvt_pk_bf16_f32 v123, v198, v199
	v_pk_mul_f32 v[100:101], v[100:101], v[178:179] op_sel_hi:[1,0]
	v_pk_fma_f32 v[110:111], v[130:131], v[196:197], v[126:127]
	v_pk_fma_f32 v[108:109], v[128:129], v[194:195], v[124:125]
	global_store_dwordx4 v[188:189], v[120:123], off nt
	v_pk_mul_f32 v[102:103], v[102:103], v[178:179] op_sel_hi:[1,0]
	v_pk_mul_f32 v[124:125], v[96:97], v[178:179] op_sel_hi:[1,0]
	v_pk_mul_f32 v[122:123], v[132:133], v[100:101]
	v_pk_mul_f32 v[126:127], v[98:99], v[178:179] op_sel_hi:[1,0]
	v_pk_fma_f32 v[96:97], v[132:133], v[100:101], v[112:113]
	v_cvt_pk_bf16_f32 v112, v122, v123
	v_pk_mul_f32 v[120:121], v[134:135], v[102:103]
	v_pk_mul_f32 v[190:191], v[130:131], v[126:127]
	v_pk_mul_f32 v[192:193], v[128:129], v[124:125]
	v_pk_fma_f32 v[98:99], v[134:135], v[102:103], v[114:115]
	v_cvt_pk_bf16_f32 v113, v120, v121
	v_cvt_pk_bf16_f32 v114, v192, v193
	v_cvt_pk_bf16_f32 v115, v190, v191
	global_store_dwordx4 v[188:189], v[112:115], off offset:256 nt
	v_pk_fma_f32 v[102:103], v[130:131], v[126:127], v[118:119]
	v_pk_fma_f32 v[100:101], v[128:129], v[124:125], v[116:117]
	v_or_b32_e32 v112, 32, v152
	v_ashrrev_i32_e32 v113, 31, v112
	v_lshlrev_b64 v[112:113], 11, v[112:113]
	v_pk_mul_f32 v[92:93], v[92:93], v[176:177] op_sel_hi:[1,0]
	v_pk_mul_f32 v[94:95], v[94:95], v[176:177] op_sel_hi:[1,0]
	v_pk_mul_f32 v[118:119], v[88:89], v[176:177] op_sel_hi:[1,0]
	v_pk_mul_f32 v[120:121], v[90:91], v[176:177] op_sel_hi:[1,0]
	v_lshl_add_u64 v[112:113], v[180:181], 0, v[112:113]
	v_pk_mul_f32 v[114:115], v[134:135], v[94:95]
	v_pk_mul_f32 v[116:117], v[132:133], v[92:93]
	v_pk_mul_f32 v[122:123], v[130:131], v[120:121]
	v_pk_mul_f32 v[124:125], v[128:129], v[118:119]
	v_pk_fma_f32 v[90:91], v[134:135], v[94:95], v[106:107]
	v_pk_fma_f32 v[88:89], v[132:133], v[92:93], v[104:105]
	v_cvt_pk_bf16_f32 v104, v116, v117
	v_cvt_pk_bf16_f32 v105, v114, v115
	v_cvt_pk_bf16_f32 v106, v124, v125
	v_cvt_pk_bf16_f32 v107, v122, v123
	v_pk_mul_f32 v[84:85], v[84:85], v[174:175] op_sel_hi:[1,0]
	v_pk_fma_f32 v[94:95], v[130:131], v[120:121], v[110:111]
	v_pk_fma_f32 v[92:93], v[128:129], v[118:119], v[108:109]
	global_store_dwordx4 v[112:113], v[104:107], off nt
	v_pk_mul_f32 v[86:87], v[86:87], v[174:175] op_sel_hi:[1,0]
	v_pk_mul_f32 v[108:109], v[80:81], v[174:175] op_sel_hi:[1,0]
	v_pk_mul_f32 v[106:107], v[132:133], v[84:85]
	v_pk_mul_f32 v[110:111], v[82:83], v[174:175] op_sel_hi:[1,0]
	v_pk_fma_f32 v[80:81], v[132:133], v[84:85], v[96:97]
	v_cvt_pk_bf16_f32 v96, v106, v107
	v_pk_mul_f32 v[104:105], v[134:135], v[86:87]
	v_pk_mul_f32 v[114:115], v[130:131], v[110:111]
	v_pk_mul_f32 v[116:117], v[128:129], v[108:109]
	v_pk_fma_f32 v[82:83], v[134:135], v[86:87], v[98:99]
	v_cvt_pk_bf16_f32 v97, v104, v105
	v_cvt_pk_bf16_f32 v98, v116, v117
	v_cvt_pk_bf16_f32 v99, v114, v115
	global_store_dwordx4 v[112:113], v[96:99], off offset:256 nt
	v_pk_fma_f32 v[86:87], v[130:131], v[110:111], v[102:103]
	v_pk_fma_f32 v[84:85], v[128:129], v[108:109], v[100:101]
	v_or_b32_e32 v96, 48, v152
	v_ashrrev_i32_e32 v97, 31, v96
	v_lshlrev_b64 v[96:97], 11, v[96:97]
	v_pk_mul_f32 v[76:77], v[76:77], v[172:173] op_sel_hi:[1,0]
	v_pk_mul_f32 v[78:79], v[78:79], v[172:173] op_sel_hi:[1,0]
	v_pk_mul_f32 v[102:103], v[72:73], v[172:173] op_sel_hi:[1,0]
	v_pk_mul_f32 v[104:105], v[74:75], v[172:173] op_sel_hi:[1,0]
	v_lshl_add_u64 v[96:97], v[180:181], 0, v[96:97]
	v_pk_mul_f32 v[98:99], v[134:135], v[78:79]
	v_pk_mul_f32 v[100:101], v[132:133], v[76:77]
	v_pk_mul_f32 v[106:107], v[130:131], v[104:105]
	v_pk_mul_f32 v[108:109], v[128:129], v[102:103]
	v_pk_fma_f32 v[74:75], v[134:135], v[78:79], v[90:91]
	v_pk_fma_f32 v[72:73], v[132:133], v[76:77], v[88:89]
	v_pk_fma_f32 v[78:79], v[130:131], v[104:105], v[94:95]
	v_pk_fma_f32 v[76:77], v[128:129], v[102:103], v[92:93]
	v_cvt_pk_bf16_f32 v88, v100, v101
	v_cvt_pk_bf16_f32 v89, v98, v99
	v_cvt_pk_bf16_f32 v90, v108, v109
	v_cvt_pk_bf16_f32 v91, v106, v107
	v_pk_mul_f32 v[68:69], v[68:69], v[170:171] op_sel_hi:[1,0]
	v_pk_mul_f32 v[70:71], v[70:71], v[170:171] op_sel_hi:[1,0]
	v_pk_mul_f32 v[92:93], v[64:65], v[170:171] op_sel_hi:[1,0]
	v_pk_mul_f32 v[94:95], v[66:67], v[170:171] op_sel_hi:[1,0]
	global_store_dwordx4 v[96:97], v[88:91], off nt
	v_pk_mul_f32 v[98:99], v[130:131], v[94:95]
	v_pk_mul_f32 v[100:101], v[128:129], v[92:93]
	v_pk_mul_f32 v[88:89], v[134:135], v[70:71]
	v_pk_mul_f32 v[90:91], v[132:133], v[68:69]
	v_pk_fma_f32 v[66:67], v[134:135], v[70:71], v[82:83]
	v_pk_fma_f32 v[64:65], v[132:133], v[68:69], v[80:81]
	v_pk_fma_f32 v[70:71], v[130:131], v[94:95], v[86:87]
	v_pk_fma_f32 v[68:69], v[128:129], v[92:93], v[84:85]
	v_cvt_pk_bf16_f32 v80, v90, v91
	v_cvt_pk_bf16_f32 v81, v88, v89
	v_cvt_pk_bf16_f32 v82, v100, v101
	v_cvt_pk_bf16_f32 v83, v98, v99
	global_store_dwordx4 v[96:97], v[80:83], off offset:256 nt
	v_pk_mul_f32 v[60:61], v[60:61], v[168:169] op_sel_hi:[1,0]
	v_pk_mul_f32 v[86:87], v[56:57], v[168:169] op_sel_hi:[1,0]
	v_pk_mul_f32 v[84:85], v[132:133], v[60:61]
	v_pk_fma_f32 v[56:57], v[132:133], v[60:61], v[72:73]
	v_pk_fma_f32 v[60:61], v[128:129], v[86:87], v[76:77]
	v_add_co_u32_e32 v76, vcc, s4, v154
	v_pk_mul_f32 v[62:63], v[62:63], v[168:169] op_sel_hi:[1,0]
	v_pk_mul_f32 v[88:89], v[58:59], v[168:169] op_sel_hi:[1,0]
	v_addc_co_u32_e32 v77, vcc, 0, v155, vcc
	v_lshl_add_u64 v[80:81], v[154:155], 0, s[20:21]
	v_pk_mul_f32 v[82:83], v[134:135], v[62:63]
	v_pk_mul_f32 v[90:91], v[130:131], v[88:89]
	v_pk_mul_f32 v[92:93], v[128:129], v[86:87]
	v_pk_fma_f32 v[58:59], v[134:135], v[62:63], v[74:75]
	v_pk_fma_f32 v[62:63], v[130:131], v[88:89], v[78:79]
	v_cvt_pk_bf16_f32 v72, v84, v85
	v_cvt_pk_bf16_f32 v73, v82, v83
	v_cvt_pk_bf16_f32 v74, v92, v93
	v_cvt_pk_bf16_f32 v75, v90, v91
	global_store_dwordx4 v[76:77], v[72:75], off nt
	v_pk_mul_f32 v[52:53], v[52:53], v[166:167] op_sel_hi:[1,0]
	v_pk_mul_f32 v[54:55], v[54:55], v[166:167] op_sel_hi:[1,0]
	v_pk_mul_f32 v[76:77], v[48:49], v[166:167] op_sel_hi:[1,0]
	v_pk_mul_f32 v[78:79], v[50:51], v[166:167] op_sel_hi:[1,0]
	v_pk_mul_f32 v[72:73], v[134:135], v[54:55]
	v_pk_mul_f32 v[74:75], v[132:133], v[52:53]
	v_pk_mul_f32 v[82:83], v[130:131], v[78:79]
	v_pk_mul_f32 v[84:85], v[128:129], v[76:77]
	v_pk_fma_f32 v[50:51], v[134:135], v[54:55], v[66:67]
	v_pk_fma_f32 v[48:49], v[132:133], v[52:53], v[64:65]
	v_pk_fma_f32 v[54:55], v[130:131], v[78:79], v[70:71]
	v_pk_fma_f32 v[52:53], v[128:129], v[76:77], v[68:69]
	v_cvt_pk_bf16_f32 v64, v74, v75
	v_cvt_pk_bf16_f32 v65, v72, v73
	v_cvt_pk_bf16_f32 v66, v84, v85
	v_cvt_pk_bf16_f32 v67, v82, v83
	global_store_dwordx4 v[80:81], v[64:67], off offset:256 nt
	v_pk_mul_f32 v[44:45], v[44:45], v[164:165] op_sel_hi:[1,0]
	v_pk_mul_f32 v[70:71], v[40:41], v[164:165] op_sel_hi:[1,0]
	s_mov_b32 s4, 0x48000
	v_pk_mul_f32 v[68:69], v[132:133], v[44:45]
	v_pk_fma_f32 v[40:41], v[132:133], v[44:45], v[56:57]
	v_pk_fma_f32 v[44:45], v[128:129], v[70:71], v[60:61]
	v_add_co_u32_e32 v60, vcc, s4, v154
	v_pk_mul_f32 v[46:47], v[46:47], v[164:165] op_sel_hi:[1,0]
	v_pk_mul_f32 v[72:73], v[42:43], v[164:165] op_sel_hi:[1,0]
	v_addc_co_u32_e32 v61, vcc, 0, v155, vcc
	v_fmamk_f32 v151, v151, 0x3c000000, v183
	v_lshl_add_u64 v[64:65], v[154:155], 0, s[54:55]
	v_pk_mul_f32 v[66:67], v[134:135], v[46:47]
	v_pk_mul_f32 v[74:75], v[130:131], v[72:73]
	v_pk_mul_f32 v[76:77], v[128:129], v[70:71]
	v_pk_fma_f32 v[42:43], v[134:135], v[46:47], v[58:59]
	v_pk_fma_f32 v[46:47], v[130:131], v[72:73], v[62:63]
	v_cvt_pk_bf16_f32 v56, v68, v69
	v_cvt_pk_bf16_f32 v57, v66, v67
	v_cvt_pk_bf16_f32 v58, v76, v77
	v_cvt_pk_bf16_f32 v59, v74, v75
	global_store_dwordx4 v[60:61], v[56:59], off nt
	v_pk_mul_f32 v[36:37], v[36:37], v[162:163] op_sel_hi:[1,0]
	v_pk_mul_f32 v[38:39], v[38:39], v[162:163] op_sel_hi:[1,0]
	v_pk_mul_f32 v[60:61], v[32:33], v[162:163] op_sel_hi:[1,0]
	v_pk_mul_f32 v[62:63], v[34:35], v[162:163] op_sel_hi:[1,0]
	v_rsq_f32_e32 v158, v151
	v_pk_mul_f32 v[56:57], v[134:135], v[38:39]
	v_pk_mul_f32 v[58:59], v[132:133], v[36:37]
	v_pk_mul_f32 v[66:67], v[130:131], v[62:63]
	v_pk_mul_f32 v[68:69], v[128:129], v[60:61]
	v_pk_fma_f32 v[34:35], v[134:135], v[38:39], v[50:51]
	v_pk_fma_f32 v[32:33], v[132:133], v[36:37], v[48:49]
	v_pk_fma_f32 v[38:39], v[130:131], v[62:63], v[54:55]
	v_pk_fma_f32 v[36:37], v[128:129], v[60:61], v[52:53]
	v_cvt_pk_bf16_f32 v48, v58, v59
	v_cvt_pk_bf16_f32 v49, v56, v57
	v_cvt_pk_bf16_f32 v50, v68, v69
	v_cvt_pk_bf16_f32 v51, v66, v67
	global_store_dwordx4 v[64:65], v[48:51], off offset:256 nt
	v_pk_mul_f32 v[28:29], v[28:29], v[160:161] op_sel_hi:[1,0]
	v_pk_mul_f32 v[54:55], v[24:25], v[160:161] op_sel_hi:[1,0]
	s_mov_b32 s4, 0x50000
	v_pk_mul_f32 v[52:53], v[132:133], v[28:29]
	v_pk_fma_f32 v[24:25], v[132:133], v[28:29], v[40:41]
	v_pk_fma_f32 v[28:29], v[128:129], v[54:55], v[44:45]
	v_add_co_u32_e32 v44, vcc, s4, v154
	v_fmamk_f32 v144, v144, 0x3c000000, v183
	v_pk_mul_f32 v[30:31], v[30:31], v[160:161] op_sel_hi:[1,0]
	v_pk_mul_f32 v[56:57], v[26:27], v[160:161] op_sel_hi:[1,0]
	v_addc_co_u32_e32 v45, vcc, 0, v155, vcc
	v_rsq_f32_e32 v144, v144
	v_lshl_add_u64 v[48:49], v[154:155], 0, s[56:57]
	v_pk_mul_f32 v[50:51], v[134:135], v[30:31]
	v_pk_mul_f32 v[58:59], v[130:131], v[56:57]
	v_pk_mul_f32 v[60:61], v[128:129], v[54:55]
	v_pk_fma_f32 v[26:27], v[134:135], v[30:31], v[42:43]
	v_pk_fma_f32 v[30:31], v[130:131], v[56:57], v[46:47]
	v_cvt_pk_bf16_f32 v40, v52, v53
	v_cvt_pk_bf16_f32 v41, v50, v51
	v_cvt_pk_bf16_f32 v42, v60, v61
	v_cvt_pk_bf16_f32 v43, v58, v59
	global_store_dwordx4 v[44:45], v[40:43], off nt
	v_pk_mul_f32 v[20:21], v[20:21], v[158:159] op_sel_hi:[1,0]
	v_pk_mul_f32 v[22:23], v[22:23], v[158:159] op_sel_hi:[1,0]
	v_pk_mul_f32 v[44:45], v[16:17], v[158:159] op_sel_hi:[1,0]
	v_pk_mul_f32 v[46:47], v[18:19], v[158:159] op_sel_hi:[1,0]
	v_pk_mul_f32 v[40:41], v[134:135], v[22:23]
	v_pk_mul_f32 v[42:43], v[132:133], v[20:21]
	v_pk_mul_f32 v[50:51], v[130:131], v[46:47]
	v_pk_mul_f32 v[52:53], v[128:129], v[44:45]
	v_pk_fma_f32 v[18:19], v[134:135], v[22:23], v[34:35]
	v_pk_fma_f32 v[16:17], v[132:133], v[20:21], v[32:33]
	v_pk_fma_f32 v[22:23], v[130:131], v[46:47], v[38:39]
	v_pk_fma_f32 v[20:21], v[128:129], v[44:45], v[36:37]
	v_cvt_pk_bf16_f32 v32, v42, v43
	v_cvt_pk_bf16_f32 v33, v40, v41
	v_cvt_pk_bf16_f32 v34, v52, v53
	v_cvt_pk_bf16_f32 v35, v50, v51
	global_store_dwordx4 v[48:49], v[32:35], off offset:256 nt
	v_pk_mul_f32 v[8:9], v[8:9], v[156:157] op_sel_hi:[1,0]
	s_mov_b32 s4, 0x58000
	v_pk_mul_f32 v[12:13], v[12:13], v[156:157] op_sel_hi:[1,0]
	v_pk_mul_f32 v[14:15], v[14:15], v[156:157] op_sel_hi:[1,0]
	v_pk_mul_f32 v[10:11], v[10:11], v[156:157] op_sel_hi:[1,0]
	v_pk_mul_f32 v[40:41], v[128:129], v[8:9]
	v_pk_fma_f32 v[8:9], v[128:129], v[8:9], v[28:29]
	v_add_co_u32_e32 v28, vcc, s4, v154
	v_lshl_add_u64 v[32:33], v[154:155], 0, s[58:59]
	v_pk_mul_f32 v[34:35], v[134:135], v[14:15]
	v_pk_mul_f32 v[36:37], v[132:133], v[12:13]
	v_pk_mul_f32 v[38:39], v[130:131], v[10:11]
	v_pk_fma_f32 v[14:15], v[134:135], v[14:15], v[26:27]
	v_pk_fma_f32 v[12:13], v[132:133], v[12:13], v[24:25]
	v_cvt_pk_bf16_f32 v24, v36, v37
	v_cvt_pk_bf16_f32 v25, v34, v35
	v_cvt_pk_bf16_f32 v26, v40, v41
	v_cvt_pk_bf16_f32 v27, v38, v39
	v_addc_co_u32_e32 v29, vcc, 0, v155, vcc
	v_pk_mul_f32 v[4:5], v[4:5], v[144:145] op_sel_hi:[1,0]
	v_pk_mul_f32 v[6:7], v[6:7], v[144:145] op_sel_hi:[1,0]
	v_pk_mul_f32 v[0:1], v[0:1], v[144:145] op_sel_hi:[1,0]
	v_pk_mul_f32 v[2:3], v[2:3], v[144:145] op_sel_hi:[1,0]
	v_pk_fma_f32 v[10:11], v[130:131], v[10:11], v[30:31]
	global_store_dwordx4 v[28:29], v[24:27], off nt
	v_pk_mul_f32 v[28:29], v[130:131], v[2:3]
	v_pk_mul_f32 v[30:31], v[128:129], v[0:1]
	v_pk_mul_f32 v[24:25], v[134:135], v[6:7]
	v_pk_mul_f32 v[26:27], v[132:133], v[4:5]
	v_pk_fma_f32 v[6:7], v[134:135], v[6:7], v[18:19]
	v_pk_fma_f32 v[4:5], v[132:133], v[4:5], v[16:17]
	v_pk_fma_f32 v[2:3], v[130:131], v[2:3], v[22:23]
	v_pk_fma_f32 v[0:1], v[128:129], v[0:1], v[20:21]
	v_cvt_pk_bf16_f32 v16, v26, v27
	v_cvt_pk_bf16_f32 v17, v24, v25
	v_cvt_pk_bf16_f32 v18, v30, v31
	v_cvt_pk_bf16_f32 v19, v28, v29
	global_store_dwordx4 v[32:33], v[16:19], off offset:256 nt
	s_cbranch_scc1 .LBB0_336
	v_cmp_eq_u32_e32 vcc, 0, v186
	v_lshl_add_u32 v202, v150, 2, s26
	v_add_f32_dpp v12, v12, v12 quad_perm:[1,0,3,2] row_mask:0xf bank_mask:0xf
	v_add_f32_dpp v13, v13, v13 quad_perm:[1,0,3,2] row_mask:0xf bank_mask:0xf
	v_add_f32_dpp v14, v14, v14 quad_perm:[1,0,3,2] row_mask:0xf bank_mask:0xf
	v_add_f32_dpp v15, v15, v15 quad_perm:[1,0,3,2] row_mask:0xf bank_mask:0xf
	v_add_f32_dpp v8, v8, v8 quad_perm:[1,0,3,2] row_mask:0xf bank_mask:0xf
	v_add_f32_dpp v9, v9, v9 quad_perm:[1,0,3,2] row_mask:0xf bank_mask:0xf
	v_add_f32_dpp v10, v10, v10 quad_perm:[1,0,3,2] row_mask:0xf bank_mask:0xf
	v_add_f32_dpp v11, v11, v11 quad_perm:[1,0,3,2] row_mask:0xf bank_mask:0xf
	v_add_f32_dpp v4, v4, v4 quad_perm:[1,0,3,2] row_mask:0xf bank_mask:0xf
	v_add_f32_dpp v5, v5, v5 quad_perm:[1,0,3,2] row_mask:0xf bank_mask:0xf
	v_add_f32_dpp v6, v6, v6 quad_perm:[1,0,3,2] row_mask:0xf bank_mask:0xf
	v_add_f32_dpp v7, v7, v7 quad_perm:[1,0,3,2] row_mask:0xf bank_mask:0xf
	v_add_f32_dpp v0, v0, v0 quad_perm:[1,0,3,2] row_mask:0xf bank_mask:0xf
	v_add_f32_dpp v1, v1, v1 quad_perm:[1,0,3,2] row_mask:0xf bank_mask:0xf
	v_add_f32_dpp v2, v2, v2 quad_perm:[1,0,3,2] row_mask:0xf bank_mask:0xf
	v_add_f32_dpp v3, v3, v3 quad_perm:[1,0,3,2] row_mask:0xf bank_mask:0xf
	v_add_f32_dpp v12, v12, v12 quad_perm:[2,3,0,1] row_mask:0xf bank_mask:0xf
	v_add_f32_dpp v13, v13, v13 quad_perm:[2,3,0,1] row_mask:0xf bank_mask:0xf
	v_add_f32_dpp v14, v14, v14 quad_perm:[2,3,0,1] row_mask:0xf bank_mask:0xf
	v_add_f32_dpp v15, v15, v15 quad_perm:[2,3,0,1] row_mask:0xf bank_mask:0xf
	v_add_f32_dpp v8, v8, v8 quad_perm:[2,3,0,1] row_mask:0xf bank_mask:0xf
	v_add_f32_dpp v9, v9, v9 quad_perm:[2,3,0,1] row_mask:0xf bank_mask:0xf
	v_add_f32_dpp v10, v10, v10 quad_perm:[2,3,0,1] row_mask:0xf bank_mask:0xf
	v_add_f32_dpp v11, v11, v11 quad_perm:[2,3,0,1] row_mask:0xf bank_mask:0xf
	v_add_f32_dpp v4, v4, v4 quad_perm:[2,3,0,1] row_mask:0xf bank_mask:0xf
	v_add_f32_dpp v5, v5, v5 quad_perm:[2,3,0,1] row_mask:0xf bank_mask:0xf
	v_add_f32_dpp v6, v6, v6 quad_perm:[2,3,0,1] row_mask:0xf bank_mask:0xf
	v_add_f32_dpp v7, v7, v7 quad_perm:[2,3,0,1] row_mask:0xf bank_mask:0xf
	v_add_f32_dpp v0, v0, v0 quad_perm:[2,3,0,1] row_mask:0xf bank_mask:0xf
	v_add_f32_dpp v1, v1, v1 quad_perm:[2,3,0,1] row_mask:0xf bank_mask:0xf
	v_add_f32_dpp v2, v2, v2 quad_perm:[2,3,0,1] row_mask:0xf bank_mask:0xf
	v_add_f32_dpp v3, v3, v3 quad_perm:[2,3,0,1] row_mask:0xf bank_mask:0xf
	v_add_f32_dpp v12, v12, v12 row_half_mirror row_mask:0xf bank_mask:0xf
	v_add_f32_dpp v13, v13, v13 row_half_mirror row_mask:0xf bank_mask:0xf
	v_add_f32_dpp v14, v14, v14 row_half_mirror row_mask:0xf bank_mask:0xf
	v_add_f32_dpp v15, v15, v15 row_half_mirror row_mask:0xf bank_mask:0xf
	v_add_f32_dpp v8, v8, v8 row_half_mirror row_mask:0xf bank_mask:0xf
	v_add_f32_dpp v9, v9, v9 row_half_mirror row_mask:0xf bank_mask:0xf
	v_add_f32_dpp v10, v10, v10 row_half_mirror row_mask:0xf bank_mask:0xf
	v_add_f32_dpp v11, v11, v11 row_half_mirror row_mask:0xf bank_mask:0xf
	v_add_f32_dpp v4, v4, v4 row_half_mirror row_mask:0xf bank_mask:0xf
	v_add_f32_dpp v5, v5, v5 row_half_mirror row_mask:0xf bank_mask:0xf
	v_add_f32_dpp v6, v6, v6 row_half_mirror row_mask:0xf bank_mask:0xf
	v_add_f32_dpp v7, v7, v7 row_half_mirror row_mask:0xf bank_mask:0xf
	v_add_f32_dpp v0, v0, v0 row_half_mirror row_mask:0xf bank_mask:0xf
	v_add_f32_dpp v1, v1, v1 row_half_mirror row_mask:0xf bank_mask:0xf
	v_add_f32_dpp v2, v2, v2 row_half_mirror row_mask:0xf bank_mask:0xf
	v_add_f32_dpp v3, v3, v3 row_half_mirror row_mask:0xf bank_mask:0xf
	v_add_f32_dpp v12, v12, v12 row_mirror row_mask:0xf bank_mask:0xf
	v_add_f32_dpp v13, v13, v13 row_mirror row_mask:0xf bank_mask:0xf
	v_add_f32_dpp v14, v14, v14 row_mirror row_mask:0xf bank_mask:0xf
	v_add_f32_dpp v15, v15, v15 row_mirror row_mask:0xf bank_mask:0xf
	v_add_f32_dpp v8, v8, v8 row_mirror row_mask:0xf bank_mask:0xf
	v_add_f32_dpp v9, v9, v9 row_mirror row_mask:0xf bank_mask:0xf
	v_add_f32_dpp v10, v10, v10 row_mirror row_mask:0xf bank_mask:0xf
	v_add_f32_dpp v11, v11, v11 row_mirror row_mask:0xf bank_mask:0xf
	v_add_f32_dpp v4, v4, v4 row_mirror row_mask:0xf bank_mask:0xf
	v_add_f32_dpp v5, v5, v5 row_mirror row_mask:0xf bank_mask:0xf
	v_add_f32_dpp v6, v6, v6 row_mirror row_mask:0xf bank_mask:0xf
	v_add_f32_dpp v7, v7, v7 row_mirror row_mask:0xf bank_mask:0xf
	v_add_f32_dpp v0, v0, v0 row_mirror row_mask:0xf bank_mask:0xf
	v_add_f32_dpp v1, v1, v1 row_mirror row_mask:0xf bank_mask:0xf
	v_add_f32_dpp v2, v2, v2 row_mirror row_mask:0xf bank_mask:0xf
	v_add_f32_dpp v3, v3, v3 row_mirror row_mask:0xf bank_mask:0xf
	s_and_saveexec_b64 s[4:5], vcc
	ds_write_b32 v202, v12
	ds_write_b32 v202, v13 offset:4
	ds_write_b32 v202, v14 offset:8
	ds_write_b32 v202, v15 offset:12
	ds_write_b32 v202, v8 offset:16
	ds_write_b32 v202, v9 offset:20
	ds_write_b32 v202, v10 offset:24
	ds_write_b32 v202, v11 offset:28
	ds_write_b32 v202, v4 offset:512
	ds_write_b32 v202, v5 offset:516
	ds_write_b32 v202, v6 offset:520
	ds_write_b32 v202, v7 offset:524
	ds_write_b32 v202, v0 offset:528
	ds_write_b32 v202, v1 offset:532
	ds_write_b32 v202, v2 offset:536
	ds_write_b32 v202, v3 offset:540
